# nt hint on final y stores of the fused down+LN epilogue, the residual x loads of the phase-7 epilogue and the phase-1 x row loads
# speedup vs baseline: 1.0305x; 1.0114x over previous
.LBB0_123:
	s_waitcnt vmcnt(0)
	v_mov_b64_e32 v[160:161], v[188:189]
	v_mov_b64_e32 v[164:165], v[184:185]
	v_mov_b64_e32 v[168:169], v[180:181]
	v_mov_b64_e32 v[172:173], v[176:177]
	s_cmpk_gt_i32 s3, 0x41ff
	v_mov_b64_e32 v[162:163], v[190:191]
	v_mov_b64_e32 v[166:167], v[186:187]
	v_mov_b64_e32 v[170:171], v[182:183]
	v_mov_b64_e32 v[174:175], v[178:179]
	s_cbranch_scc1 .LBB0_125
	s_add_i32 s20, s3, 0xffffc000
	s_cmpk_lt_i32 s3, 0x4000
	s_cselect_b32 s26, 0, 8
	s_cselect_b32 s21, s23, 0
	s_cselect_b32 s20, s3, s20
	s_add_u32 s26, s0, s26
	s_addc_u32 s27, s1, 0
	s_load_dwordx2 s[26:27], s[26:27], 0x0
	s_lshl_b64 s[20:21], s[20:21], 12
	s_waitcnt lgkmcnt(0)
	s_add_u32 s20, s26, s20
	s_addc_u32 s21, s27, s21
	global_load_dwordx4 v[160:163], v194, s[20:21] nt
	global_load_dwordx4 v[164:167], v194, s[20:21] offset:1024 nt
	global_load_dwordx4 v[168:171], v194, s[20:21] offset:2048 nt
	global_load_dwordx4 v[172:175], v194, s[20:21] offset:3072 nt

.LBB0_978:
	s_andn2_b64 vcc, exec, s[8:9]
	s_mov_b32 s25, s34
	s_lshr_b32 s27, s25, 5
	s_mul_i32 s27, s27, 0x6000
	s_add_u32 s34, s4, s27
	s_addc_u32 s35, s5, 0
	s_add_u32 s34, s34, 0x2382000
	s_addc_u32 s35, s35, 0
	s_lshl_b32 s27, s36, 10
	s_add_u32 s34, s34, s27
	s_addc_u32 s35, s35, 0
	v_and_b32_e32 v254, 0xf, v192
	v_bfe_u32 v246, v192, 4, 2
	v_bfe_u32 v247, v192, 6, 2
	v_lshlrev_b32_e32 v247, 0x5, v247
	v_lshl_add_u32 v247, v246, 2, v247
	v_lshlrev_b32_e32 v163, 0x2, v247
	global_load_dwordx4 v[112:115], v163, s[34:35]
	global_load_dwordx4 v[116:119], v163, s[34:35] offset:64
	global_load_dwordx4 v[100:103], v163, s[34:35] offset:512
	global_load_dwordx4 v[104:107], v163, s[34:35] offset:576
	v_lshrrev_b32_e32 v246, 0x8, v192
	v_lshl_add_u32 v246, v246, 6, v254
	v_lshlrev_b32_e32 v148, 0xc, v246
	v_add_u32_e32 v148, v148, v163
	v_lshlrev_b32_e32 v162, 0xb, v246
	v_lshl_add_u32 v162, v247, 1, v162
	s_lshl_b32 s27, s25, 20
	s_add_u32 s34, s12, s27
	s_addc_u32 s35, s13, 0
	s_lshl_b32 s27, s36, 10
	s_add_u32 s34, s34, s27
	s_addc_u32 s35, s35, 0
	s_lshl_b32 s27, s25, 19
	s_add_u32 s8, s2, s27
	s_addc_u32 s9, s3, 0
	s_lshl_b32 s27, s36, 9
	s_add_u32 s8, s8, s27
	s_addc_u32 s9, s9, 0
	v_add_u32_e32 v247, 0x0, v148
	global_load_dwordx4 v[168:171], v247, s[34:35] nt
	global_load_dwordx4 v[172:175], v247, s[34:35] offset:64 nt
	global_load_dwordx4 v[176:179], v247, s[34:35] offset:512 nt
	global_load_dwordx4 v[180:183], v247, s[34:35] offset:576 nt
	v_add_u32_e32 v246, 0x10000, v148
	global_load_dwordx4 v[184:187], v246, s[34:35] nt
	global_load_dwordx4 v[188:191], v246, s[34:35] offset:64 nt
	global_load_dwordx4 v[194:197], v246, s[34:35] offset:512 nt
	global_load_dwordx4 v[198:201], v246, s[34:35] offset:576 nt
	v_add_u32_e32 v247, 0x20000, v148
	global_load_dwordx4 v[202:205], v247, s[34:35] nt
	global_load_dwordx4 v[206:209], v247, s[34:35] offset:64 nt
	global_load_dwordx4 v[210:213], v247, s[34:35] offset:512 nt
	global_load_dwordx4 v[214:217], v247, s[34:35] offset:576 nt
	v_add_u32_e32 v246, 0x30000, v148
	global_load_dwordx4 v[218:221], v246, s[34:35] nt
	global_load_dwordx4 v[222:225], v246, s[34:35] offset:64 nt
	global_load_dwordx4 v[226:229], v246, s[34:35] offset:512 nt
	global_load_dwordx4 v[230:233], v246, s[34:35] offset:576 nt
	v_add_u32_e32 v247, 0x80000, v148
	global_load_dwordx4 v[234:237], v247, s[34:35] nt
	global_load_dwordx4 v[238:241], v247, s[34:35] offset:64 nt
	global_load_dwordx4 v[242:245], v247, s[34:35] offset:512 nt
	global_load_dwordx4 v[250:253], v247, s[34:35] offset:576 nt
	v_add_u32_e32 v246, 0x90000, v148
	global_load_dwordx4 v[158:161], v246, s[34:35] nt
	s_waitcnt vmcnt(20)
	v_add_u32_e32 v254, 0x0, v162
	v_pk_mul_f32 v[170:171], v[170:171], s[22:23] op_sel_hi:[1,0]
	v_pk_mul_f32 v[168:169], v[168:169], s[22:23] op_sel_hi:[1,0]
	v_pk_fma_f32 v[142:143], v[142:143], v[114:115], v[170:171]
	v_pk_fma_f32 v[140:141], v[140:141], v[112:113], v[168:169]
	s_nop 0
	global_load_dwordx4 v[168:171], v246, s[34:35] offset:64 nt
	v_cvt_pk_bf16_f32 v140, v140, v141
	v_cvt_pk_bf16_f32 v141, v142, v143
	global_store_dwordx2 v254, v[140:141], s[8:9]
	s_waitcnt vmcnt(21)
	v_pk_mul_f32 v[174:175], v[174:175], s[22:23] op_sel_hi:[1,0]
	v_pk_mul_f32 v[172:173], v[172:173], s[22:23] op_sel_hi:[1,0]
	v_pk_fma_f32 v[138:139], v[138:139], v[118:119], v[174:175]
	v_pk_fma_f32 v[136:137], v[136:137], v[116:117], v[172:173]
	s_nop 0
	global_load_dwordx4 v[172:175], v246, s[34:35] offset:512 nt
	v_cvt_pk_bf16_f32 v136, v136, v137
	v_cvt_pk_bf16_f32 v137, v138, v139
	global_store_dwordx2 v254, v[136:137], s[8:9] offset:32
	s_waitcnt vmcnt(22)
	v_pk_mul_f32 v[178:179], v[178:179], s[22:23] op_sel_hi:[1,0]
	v_pk_mul_f32 v[176:177], v[176:177], s[22:23] op_sel_hi:[1,0]
	v_pk_fma_f32 v[134:135], v[134:135], v[102:103], v[178:179]
	v_pk_fma_f32 v[132:133], v[132:133], v[100:101], v[176:177]
	s_nop 0
	global_load_dwordx4 v[176:179], v246, s[34:35] offset:576 nt
	v_cvt_pk_bf16_f32 v132, v132, v133
	v_cvt_pk_bf16_f32 v133, v134, v135
	global_store_dwordx2 v254, v[132:133], s[8:9] offset:256
	s_waitcnt vmcnt(23)
	v_pk_mul_f32 v[182:183], v[182:183], s[22:23] op_sel_hi:[1,0]
	v_pk_mul_f32 v[180:181], v[180:181], s[22:23] op_sel_hi:[1,0]
	v_pk_fma_f32 v[130:131], v[130:131], v[106:107], v[182:183]
	v_pk_fma_f32 v[128:129], v[128:129], v[104:105], v[180:181]
	s_nop 0
	v_add_u32_e32 v247, 0xa0000, v148
	global_load_dwordx4 v[180:183], v247, s[34:35] nt
	v_cvt_pk_bf16_f32 v128, v128, v129
	v_cvt_pk_bf16_f32 v129, v130, v131
	global_store_dwordx2 v254, v[128:129], s[8:9] offset:288
	s_waitcnt vmcnt(24)
	v_add_u32_e32 v255, 0x8000, v162
	v_pk_mul_f32 v[186:187], v[186:187], s[22:23] op_sel_hi:[1,0]
	v_pk_mul_f32 v[184:185], v[184:185], s[22:23] op_sel_hi:[1,0]
	v_pk_fma_f32 v[126:127], v[126:127], v[114:115], v[186:187]
	v_pk_fma_f32 v[124:125], v[124:125], v[112:113], v[184:185]
	s_nop 0
	global_load_dwordx4 v[184:187], v247, s[34:35] offset:64 nt
	v_cvt_pk_bf16_f32 v124, v124, v125
	v_cvt_pk_bf16_f32 v125, v126, v127
	global_store_dwordx2 v255, v[124:125], s[8:9]
	s_waitcnt vmcnt(25)
	v_pk_mul_f32 v[190:191], v[190:191], s[22:23] op_sel_hi:[1,0]
	v_pk_mul_f32 v[188:189], v[188:189], s[22:23] op_sel_hi:[1,0]
	v_pk_fma_f32 v[122:123], v[122:123], v[118:119], v[190:191]
	v_pk_fma_f32 v[120:121], v[120:121], v[116:117], v[188:189]
	s_nop 0
	global_load_dwordx4 v[188:191], v247, s[34:35] offset:512 nt
	v_cvt_pk_bf16_f32 v120, v120, v121
	v_cvt_pk_bf16_f32 v121, v122, v123
	global_store_dwordx2 v255, v[120:121], s[8:9] offset:32
	s_waitcnt vmcnt(26)
	v_pk_mul_f32 v[196:197], v[196:197], s[22:23] op_sel_hi:[1,0]
	v_pk_mul_f32 v[194:195], v[194:195], s[22:23] op_sel_hi:[1,0]
	v_pk_fma_f32 v[110:111], v[110:111], v[102:103], v[196:197]
	v_pk_fma_f32 v[108:109], v[108:109], v[100:101], v[194:195]
	s_nop 0
	global_load_dwordx4 v[194:197], v247, s[34:35] offset:576 nt
	v_cvt_pk_bf16_f32 v108, v108, v109
	v_cvt_pk_bf16_f32 v109, v110, v111
	global_store_dwordx2 v255, v[108:109], s[8:9] offset:256
	s_waitcnt vmcnt(27)
	v_pk_mul_f32 v[200:201], v[200:201], s[22:23] op_sel_hi:[1,0]
	v_pk_mul_f32 v[198:199], v[198:199], s[22:23] op_sel_hi:[1,0]
	v_pk_fma_f32 v[98:99], v[98:99], v[106:107], v[200:201]
	v_pk_fma_f32 v[96:97], v[96:97], v[104:105], v[198:199]
	s_nop 0
	v_add_u32_e32 v246, 0xb0000, v148
	global_load_dwordx4 v[198:201], v246, s[34:35] nt
	v_cvt_pk_bf16_f32 v96, v96, v97
	v_cvt_pk_bf16_f32 v97, v98, v99
	global_store_dwordx2 v255, v[96:97], s[8:9] offset:288
	s_waitcnt vmcnt(28)
	v_add_u32_e32 v254, 0x10000, v162
	v_pk_mul_f32 v[204:205], v[204:205], s[22:23] op_sel_hi:[1,0]
	v_pk_mul_f32 v[202:203], v[202:203], s[22:23] op_sel_hi:[1,0]
	v_pk_fma_f32 v[94:95], v[94:95], v[114:115], v[204:205]
	v_pk_fma_f32 v[92:93], v[92:93], v[112:113], v[202:203]
	s_nop 0
	global_load_dwordx4 v[202:205], v246, s[34:35] offset:64 nt
	v_cvt_pk_bf16_f32 v92, v92, v93
	v_cvt_pk_bf16_f32 v93, v94, v95
	global_store_dwordx2 v254, v[92:93], s[8:9]
	s_waitcnt vmcnt(29)
	v_pk_mul_f32 v[208:209], v[208:209], s[22:23] op_sel_hi:[1,0]
	v_pk_mul_f32 v[206:207], v[206:207], s[22:23] op_sel_hi:[1,0]
	v_pk_fma_f32 v[90:91], v[90:91], v[118:119], v[208:209]
	v_pk_fma_f32 v[88:89], v[88:89], v[116:117], v[206:207]
	s_nop 0
	global_load_dwordx4 v[206:209], v246, s[34:35] offset:512 nt
	v_cvt_pk_bf16_f32 v88, v88, v89
	v_cvt_pk_bf16_f32 v89, v90, v91
	global_store_dwordx2 v254, v[88:89], s[8:9] offset:32
	s_waitcnt vmcnt(30)
	v_pk_mul_f32 v[212:213], v[212:213], s[22:23] op_sel_hi:[1,0]
	v_pk_mul_f32 v[210:211], v[210:211], s[22:23] op_sel_hi:[1,0]
	v_pk_fma_f32 v[86:87], v[86:87], v[102:103], v[212:213]
	v_pk_fma_f32 v[84:85], v[84:85], v[100:101], v[210:211]
	s_nop 0
	global_load_dwordx4 v[210:213], v246, s[34:35] offset:576 nt
	v_cvt_pk_bf16_f32 v84, v84, v85
	v_cvt_pk_bf16_f32 v85, v86, v87
	global_store_dwordx2 v254, v[84:85], s[8:9] offset:256
	s_waitcnt vmcnt(31)
	v_pk_mul_f32 v[216:217], v[216:217], s[22:23] op_sel_hi:[1,0]
	v_pk_mul_f32 v[214:215], v[214:215], s[22:23] op_sel_hi:[1,0]
	v_pk_fma_f32 v[82:83], v[82:83], v[106:107], v[216:217]
	v_pk_fma_f32 v[80:81], v[80:81], v[104:105], v[214:215]
	s_nop 0
	v_cvt_pk_bf16_f32 v80, v80, v81
	v_cvt_pk_bf16_f32 v81, v82, v83
	global_store_dwordx2 v254, v[80:81], s[8:9] offset:288
	s_waitcnt vmcnt(31)
	v_add_u32_e32 v255, 0x18000, v162
	v_pk_mul_f32 v[220:221], v[220:221], s[22:23] op_sel_hi:[1,0]
	v_pk_mul_f32 v[218:219], v[218:219], s[22:23] op_sel_hi:[1,0]
	v_pk_fma_f32 v[78:79], v[78:79], v[114:115], v[220:221]
	v_pk_fma_f32 v[76:77], v[76:77], v[112:113], v[218:219]
	s_nop 0
	v_cvt_pk_bf16_f32 v76, v76, v77
	v_cvt_pk_bf16_f32 v77, v78, v79
	global_store_dwordx2 v255, v[76:77], s[8:9]
	s_waitcnt vmcnt(31)
	v_pk_mul_f32 v[224:225], v[224:225], s[22:23] op_sel_hi:[1,0]
	v_pk_mul_f32 v[222:223], v[222:223], s[22:23] op_sel_hi:[1,0]
	v_pk_fma_f32 v[74:75], v[74:75], v[118:119], v[224:225]
	v_pk_fma_f32 v[72:73], v[72:73], v[116:117], v[222:223]
	s_nop 0
	v_cvt_pk_bf16_f32 v72, v72, v73
	v_cvt_pk_bf16_f32 v73, v74, v75
	global_store_dwordx2 v255, v[72:73], s[8:9] offset:32
	s_waitcnt vmcnt(31)
	v_pk_mul_f32 v[228:229], v[228:229], s[22:23] op_sel_hi:[1,0]
	v_pk_mul_f32 v[226:227], v[226:227], s[22:23] op_sel_hi:[1,0]
	v_pk_fma_f32 v[70:71], v[70:71], v[102:103], v[228:229]
	v_pk_fma_f32 v[68:69], v[68:69], v[100:101], v[226:227]
	s_nop 0
	v_cvt_pk_bf16_f32 v68, v68, v69
	v_cvt_pk_bf16_f32 v69, v70, v71
	global_store_dwordx2 v255, v[68:69], s[8:9] offset:256
	s_waitcnt vmcnt(31)
	v_pk_mul_f32 v[232:233], v[232:233], s[22:23] op_sel_hi:[1,0]
	v_pk_mul_f32 v[230:231], v[230:231], s[22:23] op_sel_hi:[1,0]
	v_pk_fma_f32 v[66:67], v[66:67], v[106:107], v[232:233]
	v_pk_fma_f32 v[64:65], v[64:65], v[104:105], v[230:231]
	s_nop 0
	v_cvt_pk_bf16_f32 v64, v64, v65
	v_cvt_pk_bf16_f32 v65, v66, v67
	global_store_dwordx2 v255, v[64:65], s[8:9] offset:288
	s_waitcnt vmcnt(31)
	v_add_u32_e32 v254, 0x40000, v162
	v_pk_mul_f32 v[236:237], v[236:237], s[22:23] op_sel_hi:[1,0]
	v_pk_mul_f32 v[234:235], v[234:235], s[22:23] op_sel_hi:[1,0]
	v_pk_fma_f32 v[62:63], v[62:63], v[114:115], v[236:237]
	v_pk_fma_f32 v[60:61], v[60:61], v[112:113], v[234:235]
	s_nop 0
	v_cvt_pk_bf16_f32 v60, v60, v61
	v_cvt_pk_bf16_f32 v61, v62, v63
	global_store_dwordx2 v254, v[60:61], s[8:9]
	s_waitcnt vmcnt(31)
	v_pk_mul_f32 v[240:241], v[240:241], s[22:23] op_sel_hi:[1,0]
	v_pk_mul_f32 v[238:239], v[238:239], s[22:23] op_sel_hi:[1,0]
	v_pk_fma_f32 v[58:59], v[58:59], v[118:119], v[240:241]
	v_pk_fma_f32 v[56:57], v[56:57], v[116:117], v[238:239]
	s_nop 0
	v_cvt_pk_bf16_f32 v56, v56, v57
	v_cvt_pk_bf16_f32 v57, v58, v59
	global_store_dwordx2 v254, v[56:57], s[8:9] offset:32
	s_waitcnt vmcnt(31)
	v_pk_mul_f32 v[244:245], v[244:245], s[22:23] op_sel_hi:[1,0]
	v_pk_mul_f32 v[242:243], v[242:243], s[22:23] op_sel_hi:[1,0]
	v_pk_fma_f32 v[54:55], v[54:55], v[102:103], v[244:245]
	v_pk_fma_f32 v[52:53], v[52:53], v[100:101], v[242:243]
	s_nop 0
	v_cvt_pk_bf16_f32 v52, v52, v53
	v_cvt_pk_bf16_f32 v53, v54, v55
	global_store_dwordx2 v254, v[52:53], s[8:9] offset:256
	s_waitcnt vmcnt(31)
	v_pk_mul_f32 v[252:253], v[252:253], s[22:23] op_sel_hi:[1,0]
	v_pk_mul_f32 v[250:251], v[250:251], s[22:23] op_sel_hi:[1,0]
	v_pk_fma_f32 v[50:51], v[50:51], v[106:107], v[252:253]
	v_pk_fma_f32 v[48:49], v[48:49], v[104:105], v[250:251]
	s_nop 0
	v_cvt_pk_bf16_f32 v48, v48, v49
	v_cvt_pk_bf16_f32 v49, v50, v51
	global_store_dwordx2 v254, v[48:49], s[8:9] offset:288
	s_waitcnt vmcnt(31)
	v_add_u32_e32 v255, 0x48000, v162
	v_pk_mul_f32 v[160:161], v[160:161], s[22:23] op_sel_hi:[1,0]
	v_pk_mul_f32 v[158:159], v[158:159], s[22:23] op_sel_hi:[1,0]
	v_pk_fma_f32 v[46:47], v[46:47], v[114:115], v[160:161]
	v_pk_fma_f32 v[44:45], v[44:45], v[112:113], v[158:159]
	s_nop 0
	v_cvt_pk_bf16_f32 v44, v44, v45
	v_cvt_pk_bf16_f32 v45, v46, v47
	global_store_dwordx2 v255, v[44:45], s[8:9]
	s_waitcnt vmcnt(31)
	v_pk_mul_f32 v[170:171], v[170:171], s[22:23] op_sel_hi:[1,0]
	v_pk_mul_f32 v[168:169], v[168:169], s[22:23] op_sel_hi:[1,0]
	v_pk_fma_f32 v[42:43], v[42:43], v[118:119], v[170:171]
	v_pk_fma_f32 v[40:41], v[40:41], v[116:117], v[168:169]
	s_nop 0
	v_cvt_pk_bf16_f32 v40, v40, v41
	v_cvt_pk_bf16_f32 v41, v42, v43
	global_store_dwordx2 v255, v[40:41], s[8:9] offset:32
	s_waitcnt vmcnt(30)
	v_pk_mul_f32 v[174:175], v[174:175], s[22:23] op_sel_hi:[1,0]
	v_pk_mul_f32 v[172:173], v[172:173], s[22:23] op_sel_hi:[1,0]
	v_pk_fma_f32 v[38:39], v[38:39], v[102:103], v[174:175]
	v_pk_fma_f32 v[36:37], v[36:37], v[100:101], v[172:173]
	s_nop 0
	v_cvt_pk_bf16_f32 v36, v36, v37
	v_cvt_pk_bf16_f32 v37, v38, v39
	global_store_dwordx2 v255, v[36:37], s[8:9] offset:256
	s_waitcnt vmcnt(29)
	v_pk_mul_f32 v[178:179], v[178:179], s[22:23] op_sel_hi:[1,0]
	v_pk_mul_f32 v[176:177], v[176:177], s[22:23] op_sel_hi:[1,0]
	v_pk_fma_f32 v[34:35], v[34:35], v[106:107], v[178:179]
	v_pk_fma_f32 v[32:33], v[32:33], v[104:105], v[176:177]
	s_nop 0
	v_cvt_pk_bf16_f32 v32, v32, v33
	v_cvt_pk_bf16_f32 v33, v34, v35
	global_store_dwordx2 v255, v[32:33], s[8:9] offset:288
	s_waitcnt vmcnt(28)
	v_add_u32_e32 v254, 0x50000, v162
	v_pk_mul_f32 v[182:183], v[182:183], s[22:23] op_sel_hi:[1,0]
	v_pk_mul_f32 v[180:181], v[180:181], s[22:23] op_sel_hi:[1,0]
	v_pk_fma_f32 v[30:31], v[30:31], v[114:115], v[182:183]
	v_pk_fma_f32 v[28:29], v[28:29], v[112:113], v[180:181]
	s_nop 0
	v_cvt_pk_bf16_f32 v28, v28, v29
	v_cvt_pk_bf16_f32 v29, v30, v31
	global_store_dwordx2 v254, v[28:29], s[8:9]
	s_waitcnt vmcnt(27)
	v_pk_mul_f32 v[186:187], v[186:187], s[22:23] op_sel_hi:[1,0]
	v_pk_mul_f32 v[184:185], v[184:185], s[22:23] op_sel_hi:[1,0]
	v_pk_fma_f32 v[26:27], v[26:27], v[118:119], v[186:187]
	v_pk_fma_f32 v[24:25], v[24:25], v[116:117], v[184:185]
	s_nop 0
	v_cvt_pk_bf16_f32 v24, v24, v25
	v_cvt_pk_bf16_f32 v25, v26, v27
	global_store_dwordx2 v254, v[24:25], s[8:9] offset:32
	s_waitcnt vmcnt(26)
	v_pk_mul_f32 v[190:191], v[190:191], s[22:23] op_sel_hi:[1,0]
	v_pk_mul_f32 v[188:189], v[188:189], s[22:23] op_sel_hi:[1,0]
	v_pk_fma_f32 v[22:23], v[22:23], v[102:103], v[190:191]
	v_pk_fma_f32 v[20:21], v[20:21], v[100:101], v[188:189]
	s_nop 0
	v_cvt_pk_bf16_f32 v20, v20, v21
	v_cvt_pk_bf16_f32 v21, v22, v23
	global_store_dwordx2 v254, v[20:21], s[8:9] offset:256
	s_waitcnt vmcnt(25)
	v_pk_mul_f32 v[196:197], v[196:197], s[22:23] op_sel_hi:[1,0]
	v_pk_mul_f32 v[194:195], v[194:195], s[22:23] op_sel_hi:[1,0]
	v_pk_fma_f32 v[18:19], v[18:19], v[106:107], v[196:197]
	v_pk_fma_f32 v[16:17], v[16:17], v[104:105], v[194:195]
	s_nop 0
	v_cvt_pk_bf16_f32 v16, v16, v17
	v_cvt_pk_bf16_f32 v17, v18, v19
	global_store_dwordx2 v254, v[16:17], s[8:9] offset:288
	s_waitcnt vmcnt(24)
	v_add_u32_e32 v255, 0x58000, v162
	v_pk_mul_f32 v[200:201], v[200:201], s[22:23] op_sel_hi:[1,0]
	v_pk_mul_f32 v[198:199], v[198:199], s[22:23] op_sel_hi:[1,0]
	v_pk_fma_f32 v[14:15], v[14:15], v[114:115], v[200:201]
	v_pk_fma_f32 v[12:13], v[12:13], v[112:113], v[198:199]
	s_nop 0
	v_cvt_pk_bf16_f32 v12, v12, v13
	v_cvt_pk_bf16_f32 v13, v14, v15
	global_store_dwordx2 v255, v[12:13], s[8:9]
	s_waitcnt vmcnt(23)
	v_pk_mul_f32 v[204:205], v[204:205], s[22:23] op_sel_hi:[1,0]
	v_pk_mul_f32 v[202:203], v[202:203], s[22:23] op_sel_hi:[1,0]
	v_pk_fma_f32 v[10:11], v[10:11], v[118:119], v[204:205]
	v_pk_fma_f32 v[8:9], v[8:9], v[116:117], v[202:203]
	s_nop 0
	v_cvt_pk_bf16_f32 v8, v8, v9
	v_cvt_pk_bf16_f32 v9, v10, v11
	global_store_dwordx2 v255, v[8:9], s[8:9] offset:32
	s_waitcnt vmcnt(22)
	v_pk_mul_f32 v[208:209], v[208:209], s[22:23] op_sel_hi:[1,0]
	v_pk_mul_f32 v[206:207], v[206:207], s[22:23] op_sel_hi:[1,0]
	v_pk_fma_f32 v[6:7], v[6:7], v[102:103], v[208:209]
	v_pk_fma_f32 v[4:5], v[4:5], v[100:101], v[206:207]
	s_nop 0
	v_cvt_pk_bf16_f32 v4, v4, v5
	v_cvt_pk_bf16_f32 v5, v6, v7
	global_store_dwordx2 v255, v[4:5], s[8:9] offset:256
	s_waitcnt vmcnt(21)
	v_pk_mul_f32 v[212:213], v[212:213], s[22:23] op_sel_hi:[1,0]
	v_pk_mul_f32 v[210:211], v[210:211], s[22:23] op_sel_hi:[1,0]
	v_pk_fma_f32 v[2:3], v[2:3], v[106:107], v[212:213]
	v_pk_fma_f32 v[0:1], v[0:1], v[104:105], v[210:211]
	s_nop 0
	v_cvt_pk_bf16_f32 v0, v0, v1
	v_cvt_pk_bf16_f32 v1, v2, v3
	global_store_dwordx2 v255, v[0:1], s[8:9] offset:288
	s_mov_b64 s[8:9], -1
	s_cbranch_vccnz .LBB0_967
	s_andn2_b64 vcc, exec, s[10:11]
	s_cbranch_vccnz .LBB0_966
	s_barrier
	s_branch .LBB0_966

.LBB0_1336:
	s_or_b64 exec, exec, s[12:13]
	s_waitcnt lgkmcnt(0)
	s_barrier
	v_lshl_add_u64 v[148:149], s[18:19], 0, v[160:161]
	v_lshl_add_u64 v[150:151], s[20:21], 0, v[160:161]
	global_load_dwordx4 v[140:143], v[148:149], off
	global_load_dwordx4 v[144:147], v[150:151], off
	v_or_b32_e32 v128, s26, v168
	v_lshl_add_u32 v129, v128, 3, 0
	v_add_u32_e32 v178, 0x2000, v129
	ds_read2_b64 v[136:139], v178 offset1:16
	v_add_u32_e32 v168, s25, v128
	ds_read2_b64 v[132:135], v178 offset0:32 offset1:48
	ds_read2_b64 v[128:131], v178 offset0:128 offset1:144
	v_ashrrev_i32_e32 v169, 31, v168
	v_add_u32_e32 v152, 16, v168
	v_add_u32_e32 v154, 32, v168
	v_add_u32_e32 v156, 48, v168
	v_add_u32_e32 v158, 0x80, v168
	v_lshlrev_b64 v[166:167], 12, v[168:169]
	v_ashrrev_i32_e32 v153, 31, v152
	v_ashrrev_i32_e32 v155, 31, v154
	v_ashrrev_i32_e32 v157, 31, v156
	v_ashrrev_i32_e32 v159, 31, v158
	v_lshl_add_u64 v[166:167], s[22:23], 0, v[166:167]
	v_lshlrev_b64 v[170:171], 12, v[152:153]
	v_lshlrev_b64 v[154:155], 12, v[154:155]
	v_lshlrev_b64 v[156:157], 12, v[156:157]
	v_lshlrev_b64 v[158:159], 12, v[158:159]
	s_waitcnt lgkmcnt(2)
	v_sub_f32_e32 v123, v123, v136
	v_sub_f32_e32 v122, v122, v136
	v_sub_f32_e32 v121, v121, v136
	v_sub_f32_e32 v120, v120, v136
	v_lshl_add_u64 v[152:153], v[166:167], 0, v[160:161]
	v_lshl_add_u64 v[166:167], s[22:23], 0, v[170:171]
	v_lshl_add_u64 v[170:171], s[22:23], 0, v[154:155]
	v_lshl_add_u64 v[172:173], s[22:23], 0, v[156:157]
	v_lshl_add_u64 v[174:175], s[22:23], 0, v[158:159]
	v_sub_f32_e32 v127, v127, v138
	v_sub_f32_e32 v126, v126, v138
	v_sub_f32_e32 v125, v125, v138
	v_sub_f32_e32 v124, v124, v138
	s_waitcnt lgkmcnt(1)
	v_sub_f32_e32 v119, v119, v132
	v_sub_f32_e32 v118, v118, v132
	v_sub_f32_e32 v117, v117, v132
	v_sub_f32_e32 v116, v116, v132
	v_sub_f32_e32 v99, v99, v134
	v_sub_f32_e32 v98, v98, v134
	v_sub_f32_e32 v97, v97, v134
	v_sub_f32_e32 v96, v96, v134
	s_waitcnt lgkmcnt(0)
	v_sub_f32_e32 v67, v67, v128
	v_sub_f32_e32 v66, v66, v128
	v_sub_f32_e32 v65, v65, v128
	v_sub_f32_e32 v64, v64, v128
	v_pk_mul_f32 v[120:121], v[136:137], v[120:121] op_sel:[1,0]
	v_pk_mul_f32 v[122:123], v[136:137], v[122:123] op_sel:[1,0]
	v_lshl_add_u64 v[154:155], v[166:167], 0, v[160:161]
	v_lshl_add_u64 v[156:157], v[170:171], 0, v[160:161]
	v_lshl_add_u64 v[158:159], v[172:173], 0, v[160:161]
	v_lshl_add_u64 v[166:167], v[174:175], 0, v[160:161]
	v_pk_mul_f32 v[124:125], v[138:139], v[124:125] op_sel:[1,0]
	v_pk_mul_f32 v[126:127], v[138:139], v[126:127] op_sel:[1,0]
	v_pk_mul_f32 v[116:117], v[132:133], v[116:117] op_sel:[1,0]
	v_pk_mul_f32 v[118:119], v[132:133], v[118:119] op_sel:[1,0]
	v_pk_mul_f32 v[170:171], v[134:135], v[96:97] op_sel:[1,0]
	v_pk_mul_f32 v[172:173], v[134:135], v[98:99] op_sel:[1,0]
	v_pk_mul_f32 v[174:175], v[128:129], v[64:65] op_sel:[1,0]
	v_pk_mul_f32 v[176:177], v[128:129], v[66:67] op_sel:[1,0]
	v_sub_f32_e32 v47, v47, v130
	v_sub_f32_e32 v46, v46, v130
	v_sub_f32_e32 v45, v45, v130
	v_sub_f32_e32 v44, v44, v130
	v_pk_mul_f32 v[44:45], v[130:131], v[44:45] op_sel:[1,0]
	v_pk_mul_f32 v[46:47], v[130:131], v[46:47] op_sel:[1,0]
	v_sub_f32_e32 v93, v93, v134
	v_sub_f32_e32 v92, v92, v134
	v_sub_f32_e32 v95, v95, v134
	v_sub_f32_e32 v94, v94, v134
	v_sub_f32_e32 v57, v57, v128
	v_sub_f32_e32 v56, v56, v128
	v_sub_f32_e32 v59, v59, v128
	v_sub_f32_e32 v58, v58, v128
	v_sub_f32_e32 v33, v33, v130
	v_sub_f32_e32 v32, v32, v130
	v_sub_f32_e32 v35, v35, v130
	v_sub_f32_e32 v34, v34, v130
	s_waitcnt vmcnt(0)
	v_pk_fma_f32 v[66:67], v[142:143], v[122:123], v[146:147]
	v_pk_fma_f32 v[64:65], v[140:141], v[120:121], v[144:145]
	v_pk_fma_f32 v[98:99], v[142:143], v[126:127], v[146:147]
	v_pk_fma_f32 v[96:97], v[140:141], v[124:125], v[144:145]
	v_pk_fma_f32 v[118:119], v[142:143], v[118:119], v[146:147]
	v_pk_fma_f32 v[116:117], v[140:141], v[116:117], v[144:145]
	v_pk_fma_f32 v[122:123], v[142:143], v[172:173], v[146:147]
	v_pk_fma_f32 v[120:121], v[140:141], v[170:171], v[144:145]
	v_pk_fma_f32 v[126:127], v[142:143], v[176:177], v[146:147]
	v_pk_fma_f32 v[124:125], v[140:141], v[174:175], v[144:145]
	global_store_dwordx4 v[152:153], v[64:67], off nt
	global_store_dwordx4 v[154:155], v[96:99], off nt
	global_store_dwordx4 v[156:157], v[116:119], off nt
	global_store_dwordx4 v[158:159], v[120:123], off nt
	global_store_dwordx4 v[166:167], v[124:127], off nt
	v_pk_fma_f32 v[98:99], v[142:143], v[46:47], v[146:147]
	v_pk_fma_f32 v[96:97], v[140:141], v[44:45], v[144:145]
	ds_read2_b64 v[44:47], v178 offset0:160 offset1:176
	v_lshlrev_b64 v[64:65], 12, v[162:163]
	v_lshl_add_u64 v[64:65], s[22:23], 0, v[64:65]
	v_lshl_add_u64 v[64:65], v[64:65], 0, v[160:161]
	global_store_dwordx4 v[64:65], v[96:99], off nt
	s_waitcnt lgkmcnt(0)
	v_sub_f32_e32 v29, v29, v44
	v_sub_f32_e32 v28, v28, v44
	v_pk_mul_f32 v[28:29], v[44:45], v[28:29] op_sel:[1,0]
	v_sub_f32_e32 v31, v31, v44
	v_pk_fma_f32 v[96:97], v[140:141], v[28:29], v[144:145]
	v_add_u32_e32 v28, 0xa0, v168
	v_ashrrev_i32_e32 v29, 31, v28
	v_sub_f32_e32 v30, v30, v44
	v_lshlrev_b64 v[28:29], 12, v[28:29]
	v_pk_mul_f32 v[30:31], v[44:45], v[30:31] op_sel:[1,0]
	v_lshl_add_u64 v[28:29], s[22:23], 0, v[28:29]
	v_sub_f32_e32 v13, v13, v46
	v_sub_f32_e32 v12, v12, v46
	v_pk_fma_f32 v[98:99], v[142:143], v[30:31], v[146:147]
	v_lshl_add_u64 v[28:29], v[28:29], 0, v[160:161]
	v_pk_mul_f32 v[12:13], v[46:47], v[12:13] op_sel:[1,0]
	global_store_dwordx4 v[28:29], v[96:99], off nt
	v_sub_f32_e32 v15, v15, v46
	v_sub_f32_e32 v14, v14, v46
	v_pk_fma_f32 v[96:97], v[140:141], v[12:13], v[144:145]
	v_lshlrev_b64 v[12:13], 12, v[164:165]
	v_pk_mul_f32 v[14:15], v[46:47], v[14:15] op_sel:[1,0]
	v_lshl_add_u64 v[12:13], s[22:23], 0, v[12:13]
	v_pk_fma_f32 v[98:99], v[142:143], v[14:15], v[146:147]
	v_lshl_add_u64 v[12:13], v[12:13], 0, v[160:161]
	global_store_dwordx4 v[12:13], v[96:99], off nt
	global_load_dwordx4 v[96:99], v[148:149], off offset:64
	s_nop 0
	global_load_dwordx4 v[116:119], v[150:151], off offset:64
	v_sub_f32_e32 v15, v101, v136
	v_sub_f32_e32 v14, v100, v136
	v_sub_f32_e32 v31, v103, v136
	v_sub_f32_e32 v30, v102, v136
	v_sub_f32_e32 v67, v109, v138
	v_sub_f32_e32 v66, v108, v138
	v_sub_f32_e32 v101, v111, v138
	v_sub_f32_e32 v100, v110, v138
	v_sub_f32_e32 v103, v113, v132
	v_sub_f32_e32 v102, v112, v132
	v_sub_f32_e32 v109, v115, v132
	v_sub_f32_e32 v108, v114, v132
	v_sub_f32_e32 v113, v61, v128
	v_sub_f32_e32 v112, v60, v128
	v_sub_f32_e32 v61, v63, v128
	v_sub_f32_e32 v60, v62, v128
	v_pk_mul_f32 v[30:31], v[136:137], v[30:31] op_sel:[1,0]
	v_pk_mul_f32 v[14:15], v[136:137], v[14:15] op_sel:[1,0]
	v_pk_mul_f32 v[100:101], v[138:139], v[100:101] op_sel:[1,0]
	v_pk_mul_f32 v[66:67], v[138:139], v[66:67] op_sel:[1,0]
	v_pk_mul_f32 v[108:109], v[132:133], v[108:109] op_sel:[1,0]
	v_pk_mul_f32 v[102:103], v[132:133], v[102:103] op_sel:[1,0]
	v_pk_mul_f32 v[110:111], v[134:135], v[94:95] op_sel:[1,0]
	v_pk_mul_f32 v[114:115], v[134:135], v[92:93] op_sel:[1,0]
	v_pk_mul_f32 v[120:121], v[128:129], v[60:61] op_sel:[1,0]
	v_sub_f32_e32 v9, v9, v46
	v_sub_f32_e32 v8, v8, v46
	v_sub_f32_e32 v11, v11, v46
	v_sub_f32_e32 v10, v10, v46
	v_pk_mul_f32 v[10:11], v[46:47], v[10:11] op_sel:[1,0]
	v_pk_mul_f32 v[8:9], v[46:47], v[8:9] op_sel:[1,0]
	v_sub_f32_e32 v5, v5, v46
	v_sub_f32_e32 v4, v4, v46
	v_sub_f32_e32 v7, v7, v46
	v_sub_f32_e32 v6, v6, v46
	v_pk_mul_f32 v[6:7], v[46:47], v[6:7] op_sel:[1,0]
	v_pk_mul_f32 v[4:5], v[46:47], v[4:5] op_sel:[1,0]
	v_sub_f32_e32 v19, v19, v44
	v_sub_f32_e32 v18, v18, v44
	v_sub_f32_e32 v1, v1, v46
	v_sub_f32_e32 v0, v0, v46
	v_sub_f32_e32 v3, v3, v46
	v_sub_f32_e32 v2, v2, v46
	v_pk_mul_f32 v[2:3], v[46:47], v[2:3] op_sel:[1,0]
	v_pk_mul_f32 v[0:1], v[46:47], v[0:1] op_sel:[1,0]
	s_waitcnt vmcnt(0)
	v_pk_fma_f32 v[60:61], v[14:15], v[96:97], v[116:117]
	v_pk_fma_f32 v[62:63], v[30:31], v[98:99], v[118:119]
	v_pk_mul_f32 v[14:15], v[128:129], v[112:113] op_sel:[1,0]
	v_pk_fma_f32 v[92:93], v[66:67], v[96:97], v[116:117]
	v_pk_fma_f32 v[94:95], v[100:101], v[98:99], v[118:119]
	v_pk_fma_f32 v[100:101], v[102:103], v[96:97], v[116:117]
	v_pk_fma_f32 v[102:103], v[108:109], v[98:99], v[118:119]
	v_pk_fma_f32 v[108:109], v[114:115], v[96:97], v[116:117]
	v_pk_fma_f32 v[110:111], v[110:111], v[98:99], v[118:119]
	global_store_dwordx4 v[152:153], v[60:63], off offset:64 nt
	global_store_dwordx4 v[154:155], v[92:95], off offset:64 nt
	global_store_dwordx4 v[156:157], v[100:103], off offset:64 nt
	global_store_dwordx4 v[158:159], v[108:111], off offset:64 nt
	v_pk_fma_f32 v[60:61], v[14:15], v[96:97], v[116:117]
	v_sub_f32_e32 v15, v41, v130
	v_sub_f32_e32 v14, v40, v130
	v_pk_mul_f32 v[14:15], v[130:131], v[14:15] op_sel:[1,0]
	v_sub_f32_e32 v31, v43, v130
	v_sub_f32_e32 v30, v42, v130
	v_pk_fma_f32 v[40:41], v[14:15], v[96:97], v[116:117]
	v_sub_f32_e32 v15, v25, v44
	v_sub_f32_e32 v14, v24, v44
	v_sub_f32_e32 v25, v27, v44
	v_sub_f32_e32 v24, v26, v44
	v_pk_mul_f32 v[30:31], v[130:131], v[30:31] op_sel:[1,0]
	v_pk_mul_f32 v[26:27], v[44:45], v[24:25] op_sel:[1,0]
	v_pk_mul_f32 v[14:15], v[44:45], v[14:15] op_sel:[1,0]
	v_pk_fma_f32 v[62:63], v[120:121], v[98:99], v[118:119]
	v_pk_fma_f32 v[42:43], v[30:31], v[98:99], v[118:119]
	v_pk_fma_f32 v[24:25], v[14:15], v[96:97], v[116:117]
	v_pk_fma_f32 v[26:27], v[26:27], v[98:99], v[118:119]
	v_pk_fma_f32 v[8:9], v[96:97], v[8:9], v[116:117]
	v_pk_fma_f32 v[10:11], v[98:99], v[10:11], v[118:119]
	global_store_dwordx4 v[166:167], v[60:63], off offset:64 nt
	global_store_dwordx4 v[64:65], v[40:43], off offset:64 nt
	global_store_dwordx4 v[28:29], v[24:27], off offset:64 nt
	global_store_dwordx4 v[12:13], v[8:11], off offset:64 nt
	global_load_dwordx4 v[8:11], v[148:149], off offset:512
	s_nop 0
	global_load_dwordx4 v[24:27], v[150:151], off offset:512
	v_sub_f32_e32 v15, v73, v136
	v_sub_f32_e32 v14, v72, v136
	v_sub_f32_e32 v31, v75, v136
	v_sub_f32_e32 v30, v74, v136
	v_sub_f32_e32 v41, v89, v138
	v_sub_f32_e32 v40, v88, v138
	v_sub_f32_e32 v43, v91, v138
	v_sub_f32_e32 v42, v90, v138
	v_sub_f32_e32 v61, v105, v132
	v_sub_f32_e32 v60, v104, v132
	v_sub_f32_e32 v63, v107, v132
	v_sub_f32_e32 v62, v106, v132
	v_sub_f32_e32 v67, v85, v134
	v_sub_f32_e32 v66, v84, v134
	v_sub_f32_e32 v73, v87, v134
	v_sub_f32_e32 v72, v86, v134
	v_sub_f32_e32 v87, v39, v130
	v_sub_f32_e32 v86, v38, v130
	v_pk_mul_f32 v[30:31], v[136:137], v[30:31] op_sel:[1,0]
	v_pk_mul_f32 v[14:15], v[136:137], v[14:15] op_sel:[1,0]
	v_sub_f32_e32 v85, v37, v130
	v_sub_f32_e32 v84, v36, v130
	v_pk_mul_f32 v[42:43], v[138:139], v[42:43] op_sel:[1,0]
	v_pk_mul_f32 v[40:41], v[138:139], v[40:41] op_sel:[1,0]
	v_pk_mul_f32 v[62:63], v[132:133], v[62:63] op_sel:[1,0]
	v_pk_mul_f32 v[60:61], v[132:133], v[60:61] op_sel:[1,0]
	v_pk_mul_f32 v[72:73], v[134:135], v[72:73] op_sel:[1,0]
	v_pk_mul_f32 v[66:67], v[134:135], v[66:67] op_sel:[1,0]
	v_pk_mul_f32 v[74:75], v[128:129], v[58:59] op_sel:[1,0]
	v_pk_mul_f32 v[88:89], v[128:129], v[56:57] op_sel:[1,0]
	s_waitcnt vmcnt(0)
	v_pk_fma_f32 v[36:37], v[14:15], v[8:9], v[24:25]
	v_pk_fma_f32 v[38:39], v[30:31], v[10:11], v[26:27]
	v_pk_mul_f32 v[14:15], v[130:131], v[86:87] op_sel:[1,0]
	v_pk_fma_f32 v[40:41], v[40:41], v[8:9], v[24:25]
	v_pk_fma_f32 v[42:43], v[42:43], v[10:11], v[26:27]
	v_pk_fma_f32 v[56:57], v[60:61], v[8:9], v[24:25]
	v_pk_fma_f32 v[58:59], v[62:63], v[10:11], v[26:27]
	v_pk_fma_f32 v[60:61], v[66:67], v[8:9], v[24:25]
	v_pk_fma_f32 v[62:63], v[72:73], v[10:11], v[26:27]
	v_pk_fma_f32 v[72:73], v[88:89], v[8:9], v[24:25]
	v_pk_fma_f32 v[74:75], v[74:75], v[10:11], v[26:27]
	global_store_dwordx4 v[152:153], v[36:39], off offset:512 nt
	global_store_dwordx4 v[154:155], v[40:43], off offset:512 nt
	global_store_dwordx4 v[156:157], v[56:59], off offset:512 nt
	global_store_dwordx4 v[158:159], v[60:63], off offset:512 nt
	global_store_dwordx4 v[166:167], v[72:75], off offset:512 nt
	v_pk_fma_f32 v[38:39], v[14:15], v[10:11], v[26:27]
	v_sub_f32_e32 v15, v21, v44
	v_sub_f32_e32 v14, v20, v44
	v_sub_f32_e32 v21, v23, v44
	v_sub_f32_e32 v20, v22, v44
	v_pk_mul_f32 v[30:31], v[130:131], v[84:85] op_sel:[1,0]
	v_pk_mul_f32 v[22:23], v[44:45], v[20:21] op_sel:[1,0]
	v_pk_mul_f32 v[14:15], v[44:45], v[14:15] op_sel:[1,0]
	v_pk_fma_f32 v[36:37], v[30:31], v[8:9], v[24:25]
	v_pk_fma_f32 v[20:21], v[14:15], v[8:9], v[24:25]
	v_pk_fma_f32 v[22:23], v[22:23], v[10:11], v[26:27]
	v_pk_fma_f32 v[4:5], v[4:5], v[8:9], v[24:25]
	v_pk_fma_f32 v[6:7], v[6:7], v[10:11], v[26:27]
	global_store_dwordx4 v[64:65], v[36:39], off offset:512 nt
	global_store_dwordx4 v[28:29], v[20:23], off offset:512 nt
	global_store_dwordx4 v[12:13], v[4:7], off offset:512 nt
	global_load_dwordx4 v[4:7], v[148:149], off offset:576
	s_nop 0
	global_load_dwordx4 v[8:11], v[150:151], off offset:576
	v_sub_f32_e32 v15, v49, v136
	v_sub_f32_e32 v14, v48, v136
	v_sub_f32_e32 v21, v51, v136
	v_sub_f32_e32 v20, v50, v136
	v_sub_f32_e32 v23, v69, v138
	v_sub_f32_e32 v22, v68, v138
	v_sub_f32_e32 v25, v71, v138
	v_sub_f32_e32 v24, v70, v138
	v_sub_f32_e32 v27, v77, v132
	v_sub_f32_e32 v26, v76, v132
	v_sub_f32_e32 v31, v79, v132
	v_sub_f32_e32 v30, v78, v132
	v_sub_f32_e32 v37, v81, v134
	v_sub_f32_e32 v36, v80, v134
	v_sub_f32_e32 v39, v83, v134
	v_sub_f32_e32 v38, v82, v134
	v_sub_f32_e32 v41, v53, v128
	v_sub_f32_e32 v40, v52, v128
	v_sub_f32_e32 v43, v55, v128
	v_sub_f32_e32 v42, v54, v128
	v_sub_f32_e32 v49, v17, v44
	v_sub_f32_e32 v48, v16, v44
	v_pk_mul_f32 v[16:17], v[136:137], v[20:21] op_sel:[1,0]
	v_pk_mul_f32 v[14:15], v[136:137], v[14:15] op_sel:[1,0]
	v_pk_mul_f32 v[24:25], v[138:139], v[24:25] op_sel:[1,0]
	v_pk_mul_f32 v[20:21], v[138:139], v[22:23] op_sel:[1,0]
	v_pk_mul_f32 v[30:31], v[132:133], v[30:31] op_sel:[1,0]
	v_pk_mul_f32 v[26:27], v[132:133], v[26:27] op_sel:[1,0]
	v_pk_mul_f32 v[38:39], v[134:135], v[38:39] op_sel:[1,0]
	v_pk_mul_f32 v[36:37], v[134:135], v[36:37] op_sel:[1,0]
	v_pk_mul_f32 v[42:43], v[128:129], v[42:43] op_sel:[1,0]
	v_pk_mul_f32 v[40:41], v[128:129], v[40:41] op_sel:[1,0]
	v_pk_mul_f32 v[50:51], v[130:131], v[34:35] op_sel:[1,0]
	v_pk_mul_f32 v[52:53], v[130:131], v[32:33] op_sel:[1,0]
	s_waitcnt vmcnt(0)
	v_pk_fma_f32 v[14:15], v[14:15], v[4:5], v[8:9]
	v_pk_fma_f32 v[16:17], v[16:17], v[6:7], v[10:11]
	v_pk_fma_f32 v[20:21], v[20:21], v[4:5], v[8:9]
	v_pk_fma_f32 v[22:23], v[24:25], v[6:7], v[10:11]
	v_pk_fma_f32 v[24:25], v[26:27], v[4:5], v[8:9]
	v_pk_fma_f32 v[26:27], v[30:31], v[6:7], v[10:11]
	v_pk_fma_f32 v[30:31], v[36:37], v[4:5], v[8:9]
	v_pk_fma_f32 v[32:33], v[38:39], v[6:7], v[10:11]
	v_pk_fma_f32 v[34:35], v[40:41], v[4:5], v[8:9]
	v_pk_fma_f32 v[36:37], v[42:43], v[6:7], v[10:11]
	v_pk_fma_f32 v[38:39], v[52:53], v[4:5], v[8:9]
	v_pk_fma_f32 v[40:41], v[50:51], v[6:7], v[10:11]
	global_store_dwordx4 v[152:153], v[14:17], off offset:576 nt
	global_store_dwordx4 v[154:155], v[20:23], off offset:576 nt
	global_store_dwordx4 v[156:157], v[24:27], off offset:576 nt
	global_store_dwordx4 v[158:159], v[30:33], off offset:576 nt
	global_store_dwordx4 v[166:167], v[34:37], off offset:576 nt
	global_store_dwordx4 v[64:65], v[38:41], off offset:576 nt
	v_pk_mul_f32 v[16:17], v[44:45], v[18:19] op_sel:[1,0]
	v_pk_mul_f32 v[14:15], v[44:45], v[48:49] op_sel:[1,0]
	v_pk_fma_f32 v[16:17], v[16:17], v[6:7], v[10:11]
	v_pk_fma_f32 v[14:15], v[14:15], v[4:5], v[8:9]
	v_pk_fma_f32 v[0:1], v[0:1], v[4:5], v[8:9]
	v_pk_fma_f32 v[2:3], v[2:3], v[6:7], v[10:11]
	global_store_dwordx4 v[28:29], v[14:17], off offset:576 nt
	global_store_dwordx4 v[12:13], v[0:3], off offset:576 nt
